# v16: attention fast-loop check uses the per-lane max; cross-half permlane32 swap + max moved into the rare rescale path (3 VALU fewer per half-tile), otherwise v15
# baseline (speedup 1.0000x reference)
; __device__ __forceinline__ float xmax32(float v) { auto rr = __builtin_amdgcn_permlane32_swap(__float_as_uint(v), __float_as_uint(v), false, false); return fmaxf(__uint_as_float(rr[0]), __uint_as_float(rr[1])); }
; template <int KS>
; __device__ __forceinline__ void flash_fast_tile2(ldsp Ks, ldsp Vs, const FragMap<KS>& M, const bf16x8 (&qf)[KS], f32x16 (&o)[4], float& mc, float& l) {
;     ...
;         float m0 = fmaxf(s0[0], s0[1]), m1 = fmaxf(s0[2], s0[3]);
; #pragma unroll
;         for (int r = 4; r < 16; r += 4) { m0 = fmaxf(fmaxf(m0, s0[r]), s0[r + 1]); m1 = fmaxf(fmaxf(m1, s0[r + 2]), s0[r + 3]); }
;         const float mx = xmax32(fmaxf(m0, m1));
;         if (!__all(mx - mc <= 6.f)) {
;             const float mnew = fmaxf(mc, mx), alpha = __builtin_amdgcn_exp2f(mc - mnew);
;             mc = mnew; l *= alpha;
; #pragma unroll
;             for (int b = 0; b < 4; ++b) o[b] *= alpha;
;         }
.LBB0_439:
	s_nop 10
	v_max_f32_e32 v211, v68, v69
	v_max3_f32 v212, v66, v67, v70
	v_max3_f32 v211, v211, v72, v73
	v_max3_f32 v212, v212, v71, v74
	v_max3_f32 v211, v211, v76, v77
	v_max3_f32 v212, v212, v75, v78
	v_max3_f32 v211, v211, v80, v81
	v_max3_f32 v211, v212, v79, v211
	v_cmp_ge_f32_e32 vcc, s53, v211
	s_cmp_eq_u64 vcc, exec
	s_cbranch_scc1 .LBB0_436
	v_mov_b32_e32 v212, v211
	s_nop 1
	v_permlane32_swap_b32_e32 v211, v212
	v_max_f32_e32 v211, v211, v212
	v_max_f32_e32 v213, 0, v211
	v_sub_f32_e32 v212, 0, v213
	v_exp_f32_e32 v212, v212
	v_add_f32_e32 v206, v206, v213
	v_sub_f32_e32 v66, v66, v213
	v_sub_f32_e32 v67, v67, v213
	v_sub_f32_e32 v68, v68, v213
	v_sub_f32_e32 v69, v69, v213
	v_sub_f32_e32 v70, v70, v213
	v_sub_f32_e32 v71, v71, v213
	v_sub_f32_e32 v72, v72, v213
	v_sub_f32_e32 v73, v73, v213
	v_sub_f32_e32 v74, v74, v213
	v_sub_f32_e32 v75, v75, v213
	v_sub_f32_e32 v76, v76, v213
	v_sub_f32_e32 v77, v77, v213
	v_sub_f32_e32 v78, v78, v213
	v_sub_f32_e32 v79, v79, v213
	v_sub_f32_e32 v80, v80, v213
	v_sub_f32_e32 v81, v81, v213
	v_sub_f32_e32 v214, v214, v213
	v_sub_f32_e32 v215, v215, v213
	v_sub_f32_e32 v216, v216, v213
	v_sub_f32_e32 v217, v217, v213
	v_sub_f32_e32 v218, v218, v213
	v_sub_f32_e32 v219, v219, v213
	v_sub_f32_e32 v220, v220, v213
	v_sub_f32_e32 v221, v221, v213
	v_sub_f32_e32 v222, v222, v213
	v_sub_f32_e32 v223, v223, v213
	v_sub_f32_e32 v224, v224, v213
	v_sub_f32_e32 v225, v225, v213
	v_sub_f32_e32 v226, v226, v213
	v_sub_f32_e32 v227, v227, v213
	v_sub_f32_e32 v228, v228, v213
	v_sub_f32_e32 v229, v229, v213
	v_mul_f32_e32 v195, v195, v212
	v_pk_mul_f32 v[64:65], v[64:65], v[212:213] op_sel_hi:[1,0]
	v_pk_mul_f32 v[62:63], v[62:63], v[212:213] op_sel_hi:[1,0]
	v_pk_mul_f32 v[60:61], v[60:61], v[212:213] op_sel_hi:[1,0]
	v_pk_mul_f32 v[58:59], v[58:59], v[212:213] op_sel_hi:[1,0]
	v_pk_mul_f32 v[56:57], v[56:57], v[212:213] op_sel_hi:[1,0]
	v_pk_mul_f32 v[54:55], v[54:55], v[212:213] op_sel_hi:[1,0]
	v_pk_mul_f32 v[52:53], v[52:53], v[212:213] op_sel_hi:[1,0]
	v_pk_mul_f32 v[50:51], v[50:51], v[212:213] op_sel_hi:[1,0]
	v_pk_mul_f32 v[48:49], v[48:49], v[212:213] op_sel_hi:[1,0]
	v_pk_mul_f32 v[46:47], v[46:47], v[212:213] op_sel_hi:[1,0]
	v_pk_mul_f32 v[44:45], v[44:45], v[212:213] op_sel_hi:[1,0]
	v_pk_mul_f32 v[42:43], v[42:43], v[212:213] op_sel_hi:[1,0]
	v_pk_mul_f32 v[40:41], v[40:41], v[212:213] op_sel_hi:[1,0]
	v_pk_mul_f32 v[38:39], v[38:39], v[212:213] op_sel_hi:[1,0]
	v_pk_mul_f32 v[36:37], v[36:37], v[212:213] op_sel_hi:[1,0]
	v_pk_mul_f32 v[34:35], v[34:35], v[212:213] op_sel_hi:[1,0]
	v_pk_mul_f32 v[32:33], v[32:33], v[212:213] op_sel_hi:[1,0]
	v_pk_mul_f32 v[30:31], v[30:31], v[212:213] op_sel_hi:[1,0]
	v_pk_mul_f32 v[28:29], v[28:29], v[212:213] op_sel_hi:[1,0]
	v_pk_mul_f32 v[26:27], v[26:27], v[212:213] op_sel_hi:[1,0]
	v_pk_mul_f32 v[24:25], v[24:25], v[212:213] op_sel_hi:[1,0]
	v_pk_mul_f32 v[22:23], v[22:23], v[212:213] op_sel_hi:[1,0]
	v_pk_mul_f32 v[20:21], v[20:21], v[212:213] op_sel_hi:[1,0]
	v_pk_mul_f32 v[18:19], v[18:19], v[212:213] op_sel_hi:[1,0]
	v_pk_mul_f32 v[16:17], v[16:17], v[212:213] op_sel_hi:[1,0]
	v_pk_mul_f32 v[14:15], v[14:15], v[212:213] op_sel_hi:[1,0]
	v_pk_mul_f32 v[12:13], v[12:13], v[212:213] op_sel_hi:[1,0]
	v_pk_mul_f32 v[10:11], v[10:11], v[212:213] op_sel_hi:[1,0]
	v_pk_mul_f32 v[8:9], v[8:9], v[212:213] op_sel_hi:[1,0]
	v_pk_mul_f32 v[6:7], v[6:7], v[212:213] op_sel_hi:[1,0]
	v_pk_mul_f32 v[4:5], v[4:5], v[212:213] op_sel_hi:[1,0]
	v_pk_mul_f32 v[2:3], v[2:3], v[212:213] op_sel_hi:[1,0]
	s_branch .LBB0_436

; __device__ __forceinline__ float xmax32(float v) { auto rr = __builtin_amdgcn_permlane32_swap(__float_as_uint(v), __float_as_uint(v), false, false); return fmaxf(__uint_as_float(rr[0]), __uint_as_float(rr[1])); }
; template <int KS>
; __device__ __forceinline__ void flash_fast_tile2(ldsp Ks, ldsp Vs, const FragMap<KS>& M, const bf16x8 (&qf)[KS], f32x16 (&o)[4], float& mc, float& l) {
;     ...
;         float m0 = fmaxf(s0[0], s0[1]), m1 = fmaxf(s0[2], s0[3]);
; #pragma unroll
;         for (int r = 4; r < 16; r += 4) { m0 = fmaxf(fmaxf(m0, s0[r]), s0[r + 1]); m1 = fmaxf(fmaxf(m1, s0[r + 2]), s0[r + 3]); }
;         const float mx = xmax32(fmaxf(m0, m1));
;         if (!__all(mx - mc <= 6.f)) {
;             const float mnew = fmaxf(mc, mx), alpha = __builtin_amdgcn_exp2f(mc - mnew);
;             mc = mnew; l *= alpha;
; #pragma unroll
;             for (int b = 0; b < 4; ++b) o[b] *= alpha;
;         }
.LBB0_463:
	s_nop 10
	v_max_f32_e32 v211, v82, v83
	v_max3_f32 v213, v80, v81, v84
	v_max3_f32 v211, v211, v86, v87
	v_max3_f32 v213, v213, v85, v88
	v_max3_f32 v211, v211, v90, v91
	v_max3_f32 v213, v213, v89, v92
	v_max3_f32 v211, v211, v94, v95
	v_max3_f32 v211, v213, v93, v211
	v_cmp_ge_f32_e32 vcc, s53, v211
	s_cmp_eq_u64 vcc, exec
	s_cbranch_scc1 .LBB0_460
	v_mov_b32_e32 v213, v211
	s_nop 1
	v_permlane32_swap_b32_e32 v211, v213
	v_max_f32_e32 v211, v211, v213
	v_max_f32_e32 v253, 0, v211
	v_sub_f32_e32 v252, 0, v253
	v_exp_f32_e32 v252, v252
	v_add_f32_e32 v207, v207, v253
	v_sub_f32_e32 v80, v80, v253
	v_sub_f32_e32 v81, v81, v253
	v_sub_f32_e32 v82, v82, v253
	v_sub_f32_e32 v83, v83, v253
	v_sub_f32_e32 v84, v84, v253
	v_sub_f32_e32 v85, v85, v253
	v_sub_f32_e32 v86, v86, v253
	v_sub_f32_e32 v87, v87, v253
	v_sub_f32_e32 v88, v88, v253
	v_sub_f32_e32 v89, v89, v253
	v_sub_f32_e32 v90, v90, v253
	v_sub_f32_e32 v91, v91, v253
	v_sub_f32_e32 v92, v92, v253
	v_sub_f32_e32 v93, v93, v253
	v_sub_f32_e32 v94, v94, v253
	v_sub_f32_e32 v95, v95, v253
	v_sub_f32_e32 v214, v214, v253
	v_sub_f32_e32 v215, v215, v253
	v_sub_f32_e32 v216, v216, v253
	v_sub_f32_e32 v217, v217, v253
	v_sub_f32_e32 v218, v218, v253
	v_sub_f32_e32 v219, v219, v253
	v_sub_f32_e32 v220, v220, v253
	v_sub_f32_e32 v221, v221, v253
	v_sub_f32_e32 v222, v222, v253
	v_sub_f32_e32 v223, v223, v253
	v_sub_f32_e32 v224, v224, v253
	v_sub_f32_e32 v225, v225, v253
	v_sub_f32_e32 v226, v226, v253
	v_sub_f32_e32 v227, v227, v253
	v_sub_f32_e32 v228, v228, v253
	v_sub_f32_e32 v229, v229, v253
	v_mul_f32_e32 v195, v195, v252
	v_pk_mul_f32 v[78:79], v[78:79], v[252:253] op_sel_hi:[1,0]
	v_pk_mul_f32 v[76:77], v[76:77], v[252:253] op_sel_hi:[1,0]
	v_pk_mul_f32 v[74:75], v[74:75], v[252:253] op_sel_hi:[1,0]
	v_pk_mul_f32 v[72:73], v[72:73], v[252:253] op_sel_hi:[1,0]
	v_pk_mul_f32 v[70:71], v[70:71], v[252:253] op_sel_hi:[1,0]
	v_pk_mul_f32 v[68:69], v[68:69], v[252:253] op_sel_hi:[1,0]
	v_pk_mul_f32 v[66:67], v[66:67], v[252:253] op_sel_hi:[1,0]
	v_pk_mul_f32 v[64:65], v[64:65], v[252:253] op_sel_hi:[1,0]
	v_pk_mul_f32 v[62:63], v[62:63], v[252:253] op_sel_hi:[1,0]
	v_pk_mul_f32 v[60:61], v[60:61], v[252:253] op_sel_hi:[1,0]
	v_pk_mul_f32 v[58:59], v[58:59], v[252:253] op_sel_hi:[1,0]
	v_pk_mul_f32 v[56:57], v[56:57], v[252:253] op_sel_hi:[1,0]
	v_pk_mul_f32 v[54:55], v[54:55], v[252:253] op_sel_hi:[1,0]
	v_pk_mul_f32 v[52:53], v[52:53], v[252:253] op_sel_hi:[1,0]
	v_pk_mul_f32 v[50:51], v[50:51], v[252:253] op_sel_hi:[1,0]
	v_pk_mul_f32 v[48:49], v[48:49], v[252:253] op_sel_hi:[1,0]
	v_pk_mul_f32 v[46:47], v[46:47], v[252:253] op_sel_hi:[1,0]
	v_pk_mul_f32 v[44:45], v[44:45], v[252:253] op_sel_hi:[1,0]
	v_pk_mul_f32 v[42:43], v[42:43], v[252:253] op_sel_hi:[1,0]
	v_pk_mul_f32 v[40:41], v[40:41], v[252:253] op_sel_hi:[1,0]
	v_pk_mul_f32 v[38:39], v[38:39], v[252:253] op_sel_hi:[1,0]
	v_pk_mul_f32 v[36:37], v[36:37], v[252:253] op_sel_hi:[1,0]
	v_pk_mul_f32 v[34:35], v[34:35], v[252:253] op_sel_hi:[1,0]
	v_pk_mul_f32 v[32:33], v[32:33], v[252:253] op_sel_hi:[1,0]
	v_pk_mul_f32 v[30:31], v[30:31], v[252:253] op_sel_hi:[1,0]
	v_pk_mul_f32 v[28:29], v[28:29], v[252:253] op_sel_hi:[1,0]
	v_pk_mul_f32 v[26:27], v[26:27], v[252:253] op_sel_hi:[1,0]
	v_pk_mul_f32 v[24:25], v[24:25], v[252:253] op_sel_hi:[1,0]
	v_pk_mul_f32 v[22:23], v[22:23], v[252:253] op_sel_hi:[1,0]
	v_pk_mul_f32 v[20:21], v[20:21], v[252:253] op_sel_hi:[1,0]
	v_pk_mul_f32 v[18:19], v[18:19], v[252:253] op_sel_hi:[1,0]
	v_pk_mul_f32 v[16:17], v[16:17], v[252:253] op_sel_hi:[1,0]
	s_branch .LBB0_460
